# first 128-tile GEMM k-loop of the layer loop (.LBB0_337): next k-substep fragment reads issued ahead into a second register set
# speedup vs baseline: 1.0031x; 1.0031x over previous
.LBB0_340:
	s_setprio 2
	ds_read_b128 v[188:191], v132
	ds_read_b128 v[192:195], v133 offset:36864
	ds_read_b128 v[196:199], v133 offset:46080
	ds_read_b128 v[200:203], v132 offset:4608
	s_cmp_gt_u32 s3, 12
	ds_read_b128 v[224:227], v132 offset:32
	ds_read_b128 v[228:231], v133 offset:36896
	ds_read_b128 v[232:235], v133 offset:46112
	ds_read_b128 v[236:239], v132 offset:4640
	s_waitcnt lgkmcnt(6)
	v_mfma_f32_32x32x16_bf16 v[50:65], v[188:191], v[192:195], v[50:65]
	s_waitcnt lgkmcnt(5)
	v_mfma_f32_32x32x16_bf16 v[34:49], v[188:191], v[196:199], v[34:49]
	s_waitcnt lgkmcnt(4)
	v_mfma_f32_32x32x16_bf16 v[16:31], v[200:203], v[192:195], v[16:31]
	v_mfma_f32_32x32x16_bf16 v[0:15], v[200:203], v[196:199], v[0:15]
	ds_read_b128 v[188:191], v132 offset:64
	ds_read_b128 v[192:195], v133 offset:36928
	ds_read_b128 v[196:199], v133 offset:46144
	ds_read_b128 v[200:203], v132 offset:4672
	s_waitcnt lgkmcnt(6)
	v_mfma_f32_32x32x16_bf16 v[50:65], v[224:227], v[228:231], v[50:65]
	s_waitcnt lgkmcnt(5)
	v_mfma_f32_32x32x16_bf16 v[34:49], v[224:227], v[232:235], v[34:49]
	s_waitcnt lgkmcnt(4)
	v_mfma_f32_32x32x16_bf16 v[16:31], v[236:239], v[228:231], v[16:31]
	v_mfma_f32_32x32x16_bf16 v[0:15], v[236:239], v[232:235], v[0:15]
	ds_read_b128 v[224:227], v132 offset:96
	ds_read_b128 v[228:231], v133 offset:36960
	ds_read_b128 v[232:235], v133 offset:46176
	ds_read_b128 v[236:239], v132 offset:4704
	s_waitcnt lgkmcnt(6)
	v_mfma_f32_32x32x16_bf16 v[50:65], v[188:191], v[192:195], v[50:65]
	s_waitcnt lgkmcnt(5)
	v_mfma_f32_32x32x16_bf16 v[34:49], v[188:191], v[196:199], v[34:49]
	s_waitcnt lgkmcnt(4)
	v_mfma_f32_32x32x16_bf16 v[16:31], v[200:203], v[192:195], v[16:31]
	v_mfma_f32_32x32x16_bf16 v[0:15], v[200:203], v[196:199], v[0:15]
	s_waitcnt lgkmcnt(2)
	v_mfma_f32_32x32x16_bf16 v[50:65], v[224:227], v[228:231], v[50:65]
	s_waitcnt lgkmcnt(1)
	v_mfma_f32_32x32x16_bf16 v[34:49], v[224:227], v[232:235], v[34:49]
	s_setprio 0
	s_waitcnt vmcnt(7)
	ds_write_b128 v134, v[90:93] offset:18432
	s_waitcnt vmcnt(3)
	ds_write_b128 v134, v[110:113] offset:55296
	ds_write_b128 v134, v[98:101] offset:23040
	s_waitcnt vmcnt(2)
	ds_write_b128 v134, v[118:121] offset:59904
	ds_write_b128 v134, v[106:109] offset:27648
	s_waitcnt vmcnt(1)
	ds_write_b128 v134, v[122:125] offset:64512
	ds_write_b128 v134, v[114:117] offset:32256
	s_waitcnt vmcnt(0)
	ds_write_b128 v135, v[126:129] offset:13824
	s_waitcnt lgkmcnt(0)
	s_barrier
	v_mfma_f32_32x32x16_bf16 v[16:31], v[236:239], v[228:231], v[16:31]
	v_mfma_f32_32x32x16_bf16 v[0:15], v[236:239], v[232:235], v[0:15]
	s_cbranch_scc1 .LBB0_342
	v_add_co_u32_e32 v98, vcc, 0x240000, v138
	global_load_dwordx4 v[90:93], v[140:141], off offset:384
	s_nop 0
	v_addc_co_u32_e32 v99, vcc, 0, v139, vcc
	global_load_dwordx4 v[110:113], v[98:99], off offset:384
	v_add_co_u32_e32 v98, vcc, 0x10000, v140
	s_nop 1
	v_addc_co_u32_e32 v99, vcc, 0, v141, vcc
	v_add_co_u32_e32 v106, vcc, 0x250000, v138
	global_load_dwordx4 v[98:101], v[98:99], off offset:384
	s_nop 0
	v_addc_co_u32_e32 v107, vcc, 0, v139, vcc
	global_load_dwordx4 v[118:121], v[106:107], off offset:384
	v_add_co_u32_e32 v106, vcc, 0x20000, v140
	s_nop 1
	v_addc_co_u32_e32 v107, vcc, 0, v141, vcc
	v_add_co_u32_e32 v114, vcc, 0x260000, v138
	global_load_dwordx4 v[106:109], v[106:107], off offset:384
	s_nop 0
	v_addc_co_u32_e32 v115, vcc, 0, v139, vcc
	global_load_dwordx4 v[122:125], v[114:115], off offset:384
	v_add_co_u32_e32 v114, vcc, 0x30000, v140
	s_nop 1
	v_addc_co_u32_e32 v115, vcc, 0, v141, vcc
	v_add_co_u32_e32 v126, vcc, 0x270000, v138
	global_load_dwordx4 v[114:117], v[114:115], off offset:384
	s_nop 0
	v_addc_co_u32_e32 v127, vcc, 0, v139, vcc
	global_load_dwordx4 v[126:129], v[126:127], off offset:384
.LBB0_342:
	s_setprio 2
	ds_read_b128 v[188:191], v132 offset:18432
	ds_read_b128 v[192:195], v133 offset:55296
	ds_read_b128 v[196:199], v133 offset:64512
	ds_read_b128 v[200:203], v132 offset:23040
	s_andn2_b64 vcc, exec, s[8:9]
	ds_read_b128 v[224:227], v132 offset:18464
	ds_read_b128 v[228:231], v133 offset:55328
	ds_read_b128 v[232:235], v133 offset:64544
	ds_read_b128 v[236:239], v132 offset:23072
	s_waitcnt lgkmcnt(6)
	v_mfma_f32_32x32x16_bf16 v[50:65], v[188:191], v[192:195], v[50:65]
	s_waitcnt lgkmcnt(5)
	v_mfma_f32_32x32x16_bf16 v[34:49], v[188:191], v[196:199], v[34:49]
	s_waitcnt lgkmcnt(4)
	v_mfma_f32_32x32x16_bf16 v[16:31], v[200:203], v[192:195], v[16:31]
	v_mfma_f32_32x32x16_bf16 v[0:15], v[200:203], v[196:199], v[0:15]
	ds_read_b128 v[188:191], v132 offset:18496
	ds_read_b128 v[192:195], v133 offset:55360
	ds_read_b128 v[196:199], v133 offset:64576
	ds_read_b128 v[200:203], v132 offset:23104
	s_waitcnt lgkmcnt(6)
	v_mfma_f32_32x32x16_bf16 v[50:65], v[224:227], v[228:231], v[50:65]
	s_waitcnt lgkmcnt(5)
	v_mfma_f32_32x32x16_bf16 v[34:49], v[224:227], v[232:235], v[34:49]
	s_waitcnt lgkmcnt(4)
	v_mfma_f32_32x32x16_bf16 v[16:31], v[236:239], v[228:231], v[16:31]
	v_mfma_f32_32x32x16_bf16 v[0:15], v[236:239], v[232:235], v[0:15]
	ds_read_b128 v[224:227], v132 offset:18528
	ds_read_b128 v[228:231], v133 offset:55392
	ds_read_b128 v[232:235], v133 offset:64608
	ds_read_b128 v[236:239], v132 offset:23136
	s_waitcnt lgkmcnt(6)
	v_mfma_f32_32x32x16_bf16 v[50:65], v[188:191], v[192:195], v[50:65]
	s_waitcnt lgkmcnt(5)
	v_mfma_f32_32x32x16_bf16 v[34:49], v[188:191], v[196:199], v[34:49]
	s_waitcnt lgkmcnt(4)
	v_mfma_f32_32x32x16_bf16 v[16:31], v[200:203], v[192:195], v[16:31]
	v_mfma_f32_32x32x16_bf16 v[0:15], v[200:203], v[196:199], v[0:15]
	s_waitcnt lgkmcnt(2)
	v_mfma_f32_32x32x16_bf16 v[50:65], v[224:227], v[228:231], v[50:65]
	s_waitcnt lgkmcnt(1)
	v_mfma_f32_32x32x16_bf16 v[34:49], v[224:227], v[232:235], v[34:49]
	s_waitcnt lgkmcnt(0)
	v_mfma_f32_32x32x16_bf16 v[16:31], v[236:239], v[228:231], v[16:31]
	v_mfma_f32_32x32x16_bf16 v[0:15], v[236:239], v[232:235], v[0:15]
	s_setprio 0
	s_cbranch_vccnz .LBB0_337
	ds_write_b128 v134, v[66:69]
	ds_write_b128 v134, v[70:73] offset:36864
	ds_write_b128 v134, v[74:77] offset:4608
	ds_write_b128 v134, v[78:81] offset:41472
	ds_write_b128 v134, v[82:85] offset:9216
	ds_write_b128 v134, v[86:89] offset:46080
	ds_write_b128 v134, v[94:97] offset:13824
	ds_write_b128 v134, v[102:105] offset:50688
	s_branch .LBB0_337
